# grid barrier: non-leader workgroups poll the top-level generation word directly (skips the per-XCD re-broadcast hop), on top of the combined LRU/zero-init version
# baseline (speedup 1.0000x reference)
; __device__ __forceinline__ unsigned xb_ld(unsigned* p)              { return __hip_atomic_load(p, __ATOMIC_RELAXED, __HIP_MEMORY_SCOPE_AGENT); }
; __device__ __forceinline__ unsigned xb_add(unsigned* p, unsigned v) { return __hip_atomic_fetch_add(p, v, __ATOMIC_RELAXED, __HIP_MEMORY_SCOPE_AGENT); }
; #define XB_SPIN(cond, bar) do { unsigned _sp = 0; while (cond) { __builtin_amdgcn_s_sleep(1); \
;     if ((++_sp & 255u) == 0u) { if (xb_ld(&(bar)[XB_TMO])) break; if (_sp > XB_SPIN_CAP) { atomicAdd(&(bar)[XB_TMO], 1u); break; } } } } while (0)
; __device__ __forceinline__ void xcd_barrier(const XcdBarrier& b) {
;     ...
;         unsigned nloc = b.st[0], nx = b.st[1];
;         if (nloc == 0u) { xcd_barrier_complete(bar, b.x, nloc, nx); b.st[0] = nloc; b.st[1] = nx; }
;         const unsigned old = xb_add(&bar[XB_XSUB(b.x)], 1u);
;         const unsigned gen = old / nloc;
;         if (old + 1u == (gen + 1u) * nloc) {
;             __builtin_amdgcn_fence(__ATOMIC_RELEASE, "agent");
;             asm volatile("s_waitcnt vmcnt(0)" ::: "memory");
;             const unsigned og = xb_add(&bar[XB_TOP], 1u);
;             const unsigned tg = og / nx;
;             if (og + 1u == (tg + 1u) * nx) xb_add(&bar[XB_TOPGEN], 1u);
;             else XB_SPIN(xb_ld(&bar[XB_TOPGEN]) == tg, bar);
;             __builtin_amdgcn_fence(__ATOMIC_ACQUIRE, "agent");
;             xb_add(&bar[XB_XGEN(b.x)], 1u);
;             asm volatile("s_waitcnt vmcnt(0)" ::: "memory");
;         } else {
;             XB_SPIN(xb_ld(&bar[XB_XGEN(b.x)]) == gen, bar);
;             __builtin_amdgcn_fence(__ATOMIC_ACQUIRE, "agent");
;             asm volatile("s_waitcnt vmcnt(0)" ::: "memory");
.LBB0_349:
	s_or_b64 exec, exec, s[38:39]
	v_cvt_f32_u32_e32 v4, v2
	s_waitcnt vmcnt(0)
	v_readfirstlane_b32 s1, v3
	v_sub_u32_e32 v3, 0, v2
	v_rcp_iflag_f32_e32 v4, v4
	v_add_u32_e32 v5, s1, v1
	v_mul_f32_e32 v4, 0x4f7ffffe, v4
	v_cvt_u32_f32_e32 v4, v4
	v_mul_lo_u32 v1, v3, v4
	v_mul_hi_u32 v1, v4, v1
	v_add_u32_e32 v1, v4, v1
	v_mul_hi_u32 v1, v5, v1
	v_mul_lo_u32 v3, v1, v2
	v_sub_u32_e32 v3, v5, v3
	v_add_u32_e32 v4, 1, v1
	v_cmp_ge_u32_e32 vcc, v3, v2
	s_nop 1
	v_cndmask_b32_e32 v1, v1, v4, vcc
	v_sub_u32_e32 v4, v3, v2
	v_cndmask_b32_e32 v3, v3, v4, vcc
	v_add_u32_e32 v4, 1, v1
	v_cmp_ge_u32_e32 vcc, v3, v2
	v_add_u32_e32 v3, 1, v5
	s_nop 0
	v_cndmask_b32_e32 v1, v1, v4, vcc
	v_mul_lo_u32 v4, v2, v1
	v_add_u32_e32 v2, v4, v2
	v_cmp_ne_u32_e32 vcc, v3, v2
	s_and_saveexec_b64 s[2:3], vcc
	s_xor_b64 s[38:39], exec, s[2:3]
	s_cbranch_execz .LBB0_363
	v_readlane_b32 s2, v251, 33
	v_readlane_b32 s3, v251, 34
	s_waitcnt lgkmcnt(0)
	s_nop 3
	global_load_dword v0, v129, s[2:3] sc1
	s_waitcnt vmcnt(0)
	v_cmp_eq_u32_e32 vcc, v0, v1
	s_and_saveexec_b64 s[40:41], vcc
	s_cbranch_execz .LBB0_362
	s_mov_b32 s1, 1
	s_mov_b64 s[42:43], 0
	s_branch .LBB0_353

; __device__ __forceinline__ unsigned xb_ld(unsigned* p)              { return __hip_atomic_load(p, __ATOMIC_RELAXED, __HIP_MEMORY_SCOPE_AGENT); }
; #define XB_SPIN(cond, bar) do { unsigned _sp = 0; while (cond) { __builtin_amdgcn_s_sleep(1); \
;     if ((++_sp & 255u) == 0u) { if (xb_ld(&(bar)[XB_TMO])) break; if (_sp > XB_SPIN_CAP) { atomicAdd(&(bar)[XB_TMO], 1u); break; } } } } while (0)
; __device__ __forceinline__ void xcd_barrier(const XcdBarrier& b) {
;     ...
;             XB_SPIN(xb_ld(&bar[XB_XGEN(b.x)]) == gen, bar);
.LBB0_357:
	v_readlane_b32 s2, v251, 33
	v_readlane_b32 s3, v251, 34
	s_add_i32 s1, s1, 1
	s_mov_b64 s[48:49], -1
	s_nop 2
	global_load_dword v0, v129, s[2:3] sc1
	s_waitcnt vmcnt(0)
	v_cmp_ne_u32_e32 vcc, v0, v1
	s_orn2_b64 s[46:47], vcc, exec
	s_branch .LBB0_352

; __device__ __forceinline__ unsigned xb_ld(unsigned* p)              { return __hip_atomic_load(p, __ATOMIC_RELAXED, __HIP_MEMORY_SCOPE_AGENT); }
; __device__ __forceinline__ unsigned xb_add(unsigned* p, unsigned v) { return __hip_atomic_fetch_add(p, v, __ATOMIC_RELAXED, __HIP_MEMORY_SCOPE_AGENT); }
; #define XB_SPIN(cond, bar) do { unsigned _sp = 0; while (cond) { __builtin_amdgcn_s_sleep(1); \
;     if ((++_sp & 255u) == 0u) { if (xb_ld(&(bar)[XB_TMO])) break; if (_sp > XB_SPIN_CAP) { atomicAdd(&(bar)[XB_TMO], 1u); break; } } } } while (0)
; __device__ __forceinline__ void xcd_barrier(const XcdBarrier& b) {
;     ...
;         unsigned nloc = b.st[0], nx = b.st[1];
;         if (nloc == 0u) { xcd_barrier_complete(bar, b.x, nloc, nx); b.st[0] = nloc; b.st[1] = nx; }
;         const unsigned old = xb_add(&bar[XB_XSUB(b.x)], 1u);
;         const unsigned gen = old / nloc;
;         if (old + 1u == (gen + 1u) * nloc) {
;             __builtin_amdgcn_fence(__ATOMIC_RELEASE, "agent");
;             asm volatile("s_waitcnt vmcnt(0)" ::: "memory");
;             const unsigned og = xb_add(&bar[XB_TOP], 1u);
;             const unsigned tg = og / nx;
;             if (og + 1u == (tg + 1u) * nx) xb_add(&bar[XB_TOPGEN], 1u);
;             else XB_SPIN(xb_ld(&bar[XB_TOPGEN]) == tg, bar);
;             __builtin_amdgcn_fence(__ATOMIC_ACQUIRE, "agent");
;             xb_add(&bar[XB_XGEN(b.x)], 1u);
;             asm volatile("s_waitcnt vmcnt(0)" ::: "memory");
;         } else {
;             XB_SPIN(xb_ld(&bar[XB_XGEN(b.x)]) == gen, bar);
;             __builtin_amdgcn_fence(__ATOMIC_ACQUIRE, "agent");
;             asm volatile("s_waitcnt vmcnt(0)" ::: "memory");
.LBB0_916:
	s_or_b64 exec, exec, s[38:39]
	v_cvt_f32_u32_e32 v4, v2
	s_waitcnt vmcnt(0)
	v_readfirstlane_b32 s0, v3
	v_sub_u32_e32 v3, 0, v2
	v_rcp_iflag_f32_e32 v4, v4
	v_add_u32_e32 v5, s0, v1
	v_mul_f32_e32 v4, 0x4f7ffffe, v4
	v_cvt_u32_f32_e32 v4, v4
	v_mul_lo_u32 v1, v3, v4
	v_mul_hi_u32 v1, v4, v1
	v_add_u32_e32 v1, v4, v1
	v_mul_hi_u32 v1, v5, v1
	v_mul_lo_u32 v3, v1, v2
	v_sub_u32_e32 v3, v5, v3
	v_add_u32_e32 v4, 1, v1
	v_cmp_ge_u32_e32 vcc, v3, v2
	s_nop 1
	v_cndmask_b32_e32 v1, v1, v4, vcc
	v_sub_u32_e32 v4, v3, v2
	v_cndmask_b32_e32 v3, v3, v4, vcc
	v_add_u32_e32 v4, 1, v1
	v_cmp_ge_u32_e32 vcc, v3, v2
	v_add_u32_e32 v3, 1, v5
	s_nop 0
	v_cndmask_b32_e32 v1, v1, v4, vcc
	v_mul_lo_u32 v4, v2, v1
	v_add_u32_e32 v2, v4, v2
	v_cmp_ne_u32_e32 vcc, v3, v2
	s_and_saveexec_b64 s[0:1], vcc
	s_xor_b64 s[38:39], exec, s[0:1]
	s_cbranch_execz .LBB0_930
	v_readlane_b32 s0, v251, 33
	v_readlane_b32 s1, v251, 34
	s_waitcnt lgkmcnt(0)
	s_nop 3
	global_load_dword v0, v129, s[0:1] sc1
	s_waitcnt vmcnt(0)
	v_cmp_eq_u32_e32 vcc, v0, v1
	s_and_saveexec_b64 s[40:41], vcc
	s_cbranch_execz .LBB0_929
	s_mov_b32 s0, 1
	s_mov_b64 s[42:43], 0
	s_branch .LBB0_920

; __device__ __forceinline__ unsigned xb_ld(unsigned* p)              { return __hip_atomic_load(p, __ATOMIC_RELAXED, __HIP_MEMORY_SCOPE_AGENT); }
; #define XB_SPIN(cond, bar) do { unsigned _sp = 0; while (cond) { __builtin_amdgcn_s_sleep(1); \
;     if ((++_sp & 255u) == 0u) { if (xb_ld(&(bar)[XB_TMO])) break; if (_sp > XB_SPIN_CAP) { atomicAdd(&(bar)[XB_TMO], 1u); break; } } } } while (0)
; __device__ __forceinline__ void xcd_barrier(const XcdBarrier& b) {
;     ...
;             XB_SPIN(xb_ld(&bar[XB_XGEN(b.x)]) == gen, bar);
.LBB0_924:
	v_readlane_b32 s2, v251, 33
	v_readlane_b32 s3, v251, 34
	s_add_i32 s0, s0, 1
	s_mov_b64 s[48:49], -1
	s_nop 2
	global_load_dword v0, v129, s[2:3] sc1
	s_waitcnt vmcnt(0)
	v_cmp_ne_u32_e32 vcc, v0, v1
	s_orn2_b64 s[46:47], vcc, exec
	s_branch .LBB0_919

; __device__ __forceinline__ unsigned xb_ld(unsigned* p)              { return __hip_atomic_load(p, __ATOMIC_RELAXED, __HIP_MEMORY_SCOPE_AGENT); }
; #define XB_SPIN(cond, bar) do { unsigned _sp = 0; while (cond) { __builtin_amdgcn_s_sleep(1); \
;     if ((++_sp & 255u) == 0u) { if (xb_ld(&(bar)[XB_TMO])) break; if (_sp > XB_SPIN_CAP) { atomicAdd(&(bar)[XB_TMO], 1u); break; } } } } while (0)
; __device__ __forceinline__ void xcd_barrier(const XcdBarrier& b) {
;     ...
;             XB_SPIN(xb_ld(&bar[XB_XGEN(b.x)]) == gen, bar);
.LBB0_997:
	v_readlane_b32 s2, v251, 33
	v_readlane_b32 s3, v251, 34
	s_add_i32 s1, s1, 1
	s_mov_b64 s[50:51], -1
	s_nop 2
	global_load_dword v0, v129, s[2:3] sc1
	s_waitcnt vmcnt(0)
	v_cmp_ne_u32_e32 vcc, v0, v1
	s_orn2_b64 s[48:49], vcc, exec
	s_branch .LBB0_992

; __device__ __forceinline__ unsigned xb_ld(unsigned* p)              { return __hip_atomic_load(p, __ATOMIC_RELAXED, __HIP_MEMORY_SCOPE_AGENT); }
; #define XB_SPIN(cond, bar) do { unsigned _sp = 0; while (cond) { __builtin_amdgcn_s_sleep(1); \
;     if ((++_sp & 255u) == 0u) { if (xb_ld(&(bar)[XB_TMO])) break; if (_sp > XB_SPIN_CAP) { atomicAdd(&(bar)[XB_TMO], 1u); break; } } } } while (0)
; __device__ __forceinline__ void xcd_barrier(const XcdBarrier& b) {
;     ...
;             XB_SPIN(xb_ld(&bar[XB_XGEN(b.x)]) == gen, bar);
.LBB0_1226:
	v_readlane_b32 s2, v251, 33
	v_readlane_b32 s3, v251, 34
	s_add_i32 s0, s0, 1
	s_mov_b64 s[50:51], -1
	s_nop 2
	global_load_dword v0, v129, s[2:3] sc1
	s_waitcnt vmcnt(0)
	v_cmp_ne_u32_e32 vcc, v0, v1
	s_orn2_b64 s[48:49], vcc, exec
	s_branch .LBB0_1221

; __device__ __forceinline__ unsigned xb_ld(unsigned* p)              { return __hip_atomic_load(p, __ATOMIC_RELAXED, __HIP_MEMORY_SCOPE_AGENT); }
; __device__ __forceinline__ unsigned xb_add(unsigned* p, unsigned v) { return __hip_atomic_fetch_add(p, v, __ATOMIC_RELAXED, __HIP_MEMORY_SCOPE_AGENT); }
; #define XB_SPIN(cond, bar) do { unsigned _sp = 0; while (cond) { __builtin_amdgcn_s_sleep(1); \
;     if ((++_sp & 255u) == 0u) { if (xb_ld(&(bar)[XB_TMO])) break; if (_sp > XB_SPIN_CAP) { atomicAdd(&(bar)[XB_TMO], 1u); break; } } } } while (0)
; __device__ __forceinline__ void xcd_barrier(const XcdBarrier& b) {
;     ...
;         unsigned nloc = b.st[0], nx = b.st[1];
;         if (nloc == 0u) { xcd_barrier_complete(bar, b.x, nloc, nx); b.st[0] = nloc; b.st[1] = nx; }
;         const unsigned old = xb_add(&bar[XB_XSUB(b.x)], 1u);
;         const unsigned gen = old / nloc;
;         if (old + 1u == (gen + 1u) * nloc) {
;             __builtin_amdgcn_fence(__ATOMIC_RELEASE, "agent");
;             asm volatile("s_waitcnt vmcnt(0)" ::: "memory");
;             const unsigned og = xb_add(&bar[XB_TOP], 1u);
;             const unsigned tg = og / nx;
;             if (og + 1u == (tg + 1u) * nx) xb_add(&bar[XB_TOPGEN], 1u);
;             else XB_SPIN(xb_ld(&bar[XB_TOPGEN]) == tg, bar);
;             __builtin_amdgcn_fence(__ATOMIC_ACQUIRE, "agent");
;             xb_add(&bar[XB_XGEN(b.x)], 1u);
;             asm volatile("s_waitcnt vmcnt(0)" ::: "memory");
;         } else {
;             XB_SPIN(xb_ld(&bar[XB_XGEN(b.x)]) == gen, bar);
;             __builtin_amdgcn_fence(__ATOMIC_ACQUIRE, "agent");
;             asm volatile("s_waitcnt vmcnt(0)" ::: "memory");
.LBB0_1309:
	s_or_b64 exec, exec, s[40:41]
	v_cvt_f32_u32_e32 v4, v2
	s_waitcnt vmcnt(0)
	v_readfirstlane_b32 s0, v3
	v_sub_u32_e32 v3, 0, v2
	v_rcp_iflag_f32_e32 v4, v4
	v_add_u32_e32 v5, s0, v1
	v_mul_f32_e32 v4, 0x4f7ffffe, v4
	v_cvt_u32_f32_e32 v4, v4
	v_mul_lo_u32 v1, v3, v4
	v_mul_hi_u32 v1, v4, v1
	v_add_u32_e32 v1, v4, v1
	v_mul_hi_u32 v1, v5, v1
	v_mul_lo_u32 v3, v1, v2
	v_sub_u32_e32 v3, v5, v3
	v_add_u32_e32 v4, 1, v1
	v_cmp_ge_u32_e32 vcc, v3, v2
	s_nop 1
	v_cndmask_b32_e32 v1, v1, v4, vcc
	v_sub_u32_e32 v4, v3, v2
	v_cndmask_b32_e32 v3, v3, v4, vcc
	v_add_u32_e32 v4, 1, v1
	v_cmp_ge_u32_e32 vcc, v3, v2
	v_add_u32_e32 v3, 1, v5
	s_nop 0
	v_cndmask_b32_e32 v1, v1, v4, vcc
	v_mul_lo_u32 v4, v2, v1
	v_add_u32_e32 v2, v4, v2
	v_cmp_ne_u32_e32 vcc, v3, v2
	s_and_saveexec_b64 s[0:1], vcc
	s_xor_b64 s[40:41], exec, s[0:1]
	s_cbranch_execz .LBB0_1340
	v_readlane_b32 s0, v251, 33
	v_readlane_b32 s1, v251, 34
	s_waitcnt lgkmcnt(0)
	s_nop 3
	global_load_dword v0, v129, s[0:1] sc1
	s_waitcnt vmcnt(0)
	v_cmp_eq_u32_e32 vcc, v0, v1
	s_and_saveexec_b64 s[42:43], vcc
	s_cbranch_execz .LBB0_1339
	s_mov_b32 s0, 1
	s_mov_b64 s[44:45], 0
	s_branch .LBB0_1313

; __device__ __forceinline__ unsigned xb_ld(unsigned* p)              { return __hip_atomic_load(p, __ATOMIC_RELAXED, __HIP_MEMORY_SCOPE_AGENT); }
; __device__ __forceinline__ unsigned xb_add(unsigned* p, unsigned v) { return __hip_atomic_fetch_add(p, v, __ATOMIC_RELAXED, __HIP_MEMORY_SCOPE_AGENT); }
; #define XB_SPIN(cond, bar) do { unsigned _sp = 0; while (cond) { __builtin_amdgcn_s_sleep(1); \
;     if ((++_sp & 255u) == 0u) { if (xb_ld(&(bar)[XB_TMO])) break; if (_sp > XB_SPIN_CAP) { atomicAdd(&(bar)[XB_TMO], 1u); break; } } } } while (0)
; __device__ __forceinline__ void xcd_barrier(const XcdBarrier& b) {
;     ...
;         unsigned nloc = b.st[0], nx = b.st[1];
;         if (nloc == 0u) { xcd_barrier_complete(bar, b.x, nloc, nx); b.st[0] = nloc; b.st[1] = nx; }
;         const unsigned old = xb_add(&bar[XB_XSUB(b.x)], 1u);
;         const unsigned gen = old / nloc;
;         if (old + 1u == (gen + 1u) * nloc) {
;             __builtin_amdgcn_fence(__ATOMIC_RELEASE, "agent");
;             asm volatile("s_waitcnt vmcnt(0)" ::: "memory");
;             const unsigned og = xb_add(&bar[XB_TOP], 1u);
;             const unsigned tg = og / nx;
;             if (og + 1u == (tg + 1u) * nx) xb_add(&bar[XB_TOPGEN], 1u);
;             else XB_SPIN(xb_ld(&bar[XB_TOPGEN]) == tg, bar);
;             __builtin_amdgcn_fence(__ATOMIC_ACQUIRE, "agent");
;             xb_add(&bar[XB_XGEN(b.x)], 1u);
;             asm volatile("s_waitcnt vmcnt(0)" ::: "memory");
;         } else {
;             XB_SPIN(xb_ld(&bar[XB_XGEN(b.x)]) == gen, bar);
;             __builtin_amdgcn_fence(__ATOMIC_ACQUIRE, "agent");
;             asm volatile("s_waitcnt vmcnt(0)" ::: "memory");
.LBB0_1326:
	s_or_b64 exec, exec, s[26:27]
	v_cvt_f32_u32_e32 v4, v2
	s_waitcnt vmcnt(0)
	v_readfirstlane_b32 s0, v3
	v_sub_u32_e32 v3, 0, v2
	v_rcp_iflag_f32_e32 v4, v4
	v_add_u32_e32 v5, s0, v1
	v_mul_f32_e32 v4, 0x4f7ffffe, v4
	v_cvt_u32_f32_e32 v4, v4
	v_mul_lo_u32 v1, v3, v4
	v_mul_hi_u32 v1, v4, v1
	v_add_u32_e32 v1, v4, v1
	v_mul_hi_u32 v1, v5, v1
	v_mul_lo_u32 v3, v1, v2
	v_sub_u32_e32 v3, v5, v3
	v_add_u32_e32 v4, 1, v1
	v_cmp_ge_u32_e32 vcc, v3, v2
	s_nop 1
	v_cndmask_b32_e32 v1, v1, v4, vcc
	v_sub_u32_e32 v4, v3, v2
	v_cndmask_b32_e32 v3, v3, v4, vcc
	v_add_u32_e32 v4, 1, v1
	v_cmp_ge_u32_e32 vcc, v3, v2
	v_add_u32_e32 v3, 1, v5
	s_nop 0
	v_cndmask_b32_e32 v1, v1, v4, vcc
	v_mul_lo_u32 v4, v2, v1
	v_add_u32_e32 v2, v4, v2
	v_cmp_ne_u32_e32 vcc, v3, v2
	s_and_saveexec_b64 s[0:1], vcc
	s_xor_b64 s[26:27], exec, s[0:1]
	s_cbranch_execz .LBB0_1357
	v_readlane_b32 s0, v251, 33
	v_readlane_b32 s1, v251, 34
	s_waitcnt lgkmcnt(0)
	s_nop 3
	global_load_dword v0, v129, s[0:1] sc1
	s_waitcnt vmcnt(0)
	v_cmp_eq_u32_e32 vcc, v0, v1
	s_and_saveexec_b64 s[38:39], vcc
	s_cbranch_execz .LBB0_1356
	s_mov_b32 s0, 1
	s_mov_b64 s[40:41], 0
	s_branch .LBB0_1330

; __device__ __forceinline__ unsigned xb_ld(unsigned* p)              { return __hip_atomic_load(p, __ATOMIC_RELAXED, __HIP_MEMORY_SCOPE_AGENT); }
; #define XB_SPIN(cond, bar) do { unsigned _sp = 0; while (cond) { __builtin_amdgcn_s_sleep(1); \
;     if ((++_sp & 255u) == 0u) { if (xb_ld(&(bar)[XB_TMO])) break; if (_sp > XB_SPIN_CAP) { atomicAdd(&(bar)[XB_TMO], 1u); break; } } } } while (0)
; __device__ __forceinline__ void xcd_barrier(const XcdBarrier& b) {
;     ...
;             XB_SPIN(xb_ld(&bar[XB_XGEN(b.x)]) == gen, bar);
.LBB0_1334:
	v_readlane_b32 s2, v251, 33
	v_readlane_b32 s3, v251, 34
	s_add_i32 s0, s0, 1
	s_mov_b64 s[46:47], -1
	s_nop 2
	global_load_dword v0, v129, s[2:3] sc1
	s_waitcnt vmcnt(0)
	v_cmp_ne_u32_e32 vcc, v0, v1
	s_orn2_b64 s[44:45], vcc, exec
	s_branch .LBB0_1329
